# sliding-window attention item decode: query-tile index taken from the low bits so the 8 query heads sharing a kv head (and the M-tile's rows) land on one XCD
# speedup vs baseline: 1.0077x; 1.0077x over previous
;   DI bf16_t* z() const { return (bf16_t*)(ws + OFF_Z); }
;   DI bf16_t* vt0() const { return (bf16_t*)(ws + OFF_VT0); }
; DI int otid() { int t = threadIdx.x; asm volatile("" : "+v"(t)); return t; }
; #define ATTN_LOAD(KT) { ATTN_LOAD_K(KT); ATTN_LOAD_V(KT); }
; #define ATTN_STORE(ST) { ATTN_STORE_K(ST); ATTN_STORE_V(ST); }
; template <int DQK, int NMAP, int DV> ...
;     ...
;   ATTN_LOAD(kt_lo);
;   ATTN_STORE(0);
;   if (kt_lo < kt_hi) ATTN_LOAD(kt_lo + 1);
;   const int qmin = q0 + 32 * w, qmax = qmin + 31, qpos = qmin + l32;
; DI void swa_item(const Params& p, int it, char* smem) {
;   const int qh = it & 15, qt = (it >> 4) & 15, b = it >> 8, kvh = qh >> 3;
;   const int tid_ = otid(), lane = tid_ & 63, w = tid_ >> 6, l32 = lane & 31, g = lane >> 5;
;   f32x16 O[1][2]; float ls[1];
;   const bf16_t* zb = p.z() + (size_t)b * S * LDZ0;
;   attn_core<64, 1, 64>(zb + 2048 + qh * 64, LDZ0, zb + 3072 + kvh * 64, LDZ0, 64, nullptr, 0, p.vt0() + (size_t)(b * 2 + kvh) * 64 * S,
;                        qt * 256, max(0, qt * 4 - 2), qt * 4 + 3, 0.125f * LOG2E, p.sinks[qh] * LOG2E, 1.f, 128, smem, O, ls);
.LBB0_198:
	s_and_b32 s98, s42, 0xffffff00
	s_and_b32 s99, s42, 15
	s_lshl_b32 s99, s99, 4
	s_or_b32 s98, s98, s99
	s_bfe_u32 s99, s42, 0x40004
	s_or_b32 s98, s98, s99
	s_ashr_i32 s24, s98, 8
	s_and_b32 s43, s98, 15
	s_bfe_u32 s7, s98, 0x40004
	s_bfe_u32 s10, s98, 0x10003
	s_mul_i32 s5, s24, 0x2200000
	s_mul_hi_i32 s4, s24, 0x2200000
	s_add_u32 s0, s28, s5
	s_addc_u32 s1, s29, s4
	s_lshl_b32 s6, s43, 7
	s_add_u32 s6, s0, s6
	s_addc_u32 s25, s1, 0
	s_add_u32 s26, s6, 0x1000
	s_addc_u32 s27, s25, 0
	s_lshl_b32 s6, s10, 7
	s_add_u32 s0, s0, s6
	s_addc_u32 s1, s1, 0
	s_add_u32 s0, s0, 0x1800
	s_addc_u32 s1, s1, 0
	s_lshl_b32 s6, s24, 1
	s_or_b32 s44, s6, s10
	s_ashr_i32 s45, s44, 31
	s_lshl_b64 s[44:45], s[44:45], 19
	s_add_u32 s46, s2, s44
	s_addc_u32 s47, s3, s45
	s_lshl_b32 s44, s7, 8
	s_lshl_b32 s10, s7, 2
	s_lshl_b32 s7, s43, 2
	v_readlane_b32 s48, v252, 4
	v_mov_b32_e32 v110, v206
	v_mov_b32_e32 v1, s7
	v_readlane_b32 s54, v252, 10
	v_readlane_b32 s55, v252, 11
	v_mov_b64_e32 v[2:3], s[26:27]
	v_mov_b32_e32 v5, v0
	v_sub_u32_e64 v13, s10, 2 clamp
	v_mov_b64_e32 v[6:7], s[0:1]
	s_nop 0
	global_load_dword v11, v1, s[54:55]
	v_mov_b32_e32 v1, v206
	v_lshlrev_b32_e32 v18, 7, v13
	v_readfirstlane_b32 s7, v1
	s_ashr_i32 s7, s7, 1
	s_andn2_b32 s7, s7, 31
	v_and_b32_e32 v10, 31, v1
	s_add_i32 s25, s7, s44
	v_bfe_u32 v12, v1, 5, 1
	v_or_b32_e32 v4, s25, v10
	v_mad_i64_i32 v[2:3], s[26:27], v4, s30, v[2:3]
	v_lshlrev_b32_e32 v4, 4, v12
	v_lshl_add_u64 v[14:15], v[2:3], 0, v[4:5]
	v_ashrrev_i32_e32 v2, 31, v1
	v_lshrrev_b32_e32 v2, 29, v2
	v_add_u32_e32 v16, v1, v2
	v_ashrrev_i32_e32 v2, 3, v16
	v_ashrrev_i32_e32 v3, 31, v2
	v_lshlrev_b32_e32 v4, 6, v13
	v_lshl_add_u64 v[4:5], v[4:5], 0, v[2:3]
	v_mad_u64_u32 v[8:9], s[26:27], v4, s30, v[6:7]
	v_and_b32_e32 v4, -8, v16
	v_sub_u32_e32 v20, v1, v4
	v_lshlrev_b32_e32 v6, 3, v20
	v_mad_i32_i24 v9, v5, s30, v9
	v_ashrrev_i32_e32 v7, 31, v6
	v_ashrrev_i32_e32 v16, 3, v1
	v_lshl_add_u64 v[4:5], v[6:7], 1, v[8:9]
	v_ashrrev_i32_e32 v17, 31, v16
	global_load_dwordx4 v[80:83], v[14:15], off offset:96
	global_load_dwordx4 v[84:87], v[4:5], off
	v_lshlrev_b64 v[4:5], 13, v[16:17]
	v_lshl_add_u64 v[8:9], s[46:47], 0, v[4:5]
	v_mov_b32_e32 v19, v0
	v_lshlrev_b32_e32 v17, 4, v1
	v_lshl_add_u64 v[8:9], v[8:9], 0, v[18:19]
	v_and_b32_e32 v18, 0x70, v17
	v_lshl_add_u64 v[8:9], v[8:9], 0, v[18:19]
	global_load_dwordx4 v[88:91], v[14:15], off
	global_load_dwordx4 v[100:103], v[8:9], off
	global_load_dwordx4 v[92:95], v[14:15], off offset:32
	global_load_dwordx4 v[96:99], v[14:15], off offset:64
	s_or_b32 s45, s10, 3
	v_cmp_le_u32_e32 vcc, s45, v13
	v_mul_lo_u32 v14, v16, s33
	v_mul_lo_u32 v15, v2, s31
	v_lshlrev_b32_e32 v16, 4, v20
	s_and_b64 vcc, exec, vcc
	v_add3_u32 v111, 16, v14, v18
	v_add3_u32 v112, 16, v15, v16
	v_readlane_b32 s49, v252, 5
	v_readlane_b32 s50, v252, 6
	v_readlane_b32 s51, v252, 7
	v_readlane_b32 s52, v252, 8
	v_readlane_b32 s53, v252, 9
	v_readlane_b32 s56, v252, 12
	v_readlane_b32 s57, v252, 13
	v_readlane_b32 s58, v252, 14
	v_readlane_b32 s59, v252, 15
	v_readlane_b32 s60, v252, 16
	v_readlane_b32 s61, v252, 17
	v_readlane_b32 s62, v252, 18
	v_readlane_b32 s63, v252, 19
	v_add_u32_e32 v14, 0x2400, v111
	s_waitcnt vmcnt(4)
	ds_write_b128 v112, v[84:87]
	s_waitcnt vmcnt(2)
	ds_write2_b64 v14, v[100:101], v[102:103] offset1:1
	s_cbranch_vccnz .LBB0_200
	s_max_u32 s10, s10, 2
	s_add_i32 s10, s10, -1
	s_lshl_b64 s[26:27], s[10:11], 6
	v_lshl_add_u64 v[14:15], s[26:27], 0, v[2:3]
	v_mov_b64_e32 v[16:17], s[0:1]
	v_mad_u64_u32 v[16:17], s[0:1], v14, s30, v[16:17]
	v_mad_i32_i24 v17, v15, s30, v17
	v_lshl_add_u64 v[14:15], v[6:7], 1, v[16:17]
	global_load_dwordx4 v[84:87], v[14:15], off
	global_load_dwordx4 v[100:103], v[8:9], off offset:128
.LBB0_200:
	v_cmp_lt_u32_e32 vcc, s45, v13
	v_cmp_eq_u32_e64 s[0:1], 0, v12
	v_mov_b32_e32 v31, 0
	s_nop 0
	v_cndmask_b32_e64 v119, 0, 1.0, s[0:1]
	s_cbranch_vccnz .LBB0_196
	s_lshr_b32 s0, s98, 4
	s_and_b32 s0, s0, 15
	s_or_b32 s10, s25, 31
	s_lshl_b32 s1, s0, 2
	s_cmp_gt_u32 s1, 2
	s_cselect_b32 s26, s1, 2
	s_max_u32 s1, s1, 2
	s_bfe_u32 s51, s98, 0x10003
	s_lshl_b32 s53, s1, 6
	s_mul_hi_u32 s27, s26, 0x88000
	s_mul_i32 s50, s26, 0x88000
	s_lshl_b32 s52, s51, 7
	s_add_i32 s46, s53, 0xffffff80
	s_lshl_b32 s54, s0, 8
	s_lshl_b32 s26, s26, 7
	s_add_i32 s47, s1, -1
	s_add_i32 s48, s25, 0xffffff80
	s_add_i32 s49, s25, 0xffffff9f
	s_add_u32 s0, s5, s50
	s_addc_u32 s1, s4, s27
	s_add_u32 s0, s52, s0
	s_addc_u32 s1, 0, s1
	v_mov_b64_e32 v[8:9], s[0:1]
	v_mad_i64_i32 v[2:3], s[0:1], v2, s30, v[8:9]
	s_add_i32 s0, s54, s7
	v_lshl_add_u64 v[2:3], v[6:7], 1, v[2:3]
	s_addk_i32 s0, 0x80
	v_lshl_add_u64 v[104:105], s[8:9], 0, v[2:3]
	v_add_u32_e32 v2, s0, v10
	s_add_i32 s0, s51, s6
	s_ashr_i32 s1, s0, 31
	v_lshlrev_b32_e32 v115, 2, v12
	s_lshl_b64 s[0:1], s[0:1], 19
	v_sub_u32_e32 v2, v2, v115
	s_or_b32 s0, s0, s26
	v_and_b32_e32 v1, 7, v1
	v_subrev_u32_e32 v117, s53, v2
	v_lshl_add_u64 v[2:3], s[0:1], 0, v[4:5]
	v_lshlrev_b32_e32 v4, 4, v1
	v_mov_b32_e32 v5, v0
	v_lshlrev_b32_e32 v13, 3, v12
	v_lshl_add_u64 v[2:3], v[2:3], 0, v[4:5]
	v_mov_b32_e32 v32, 0
	v_mul_f32_e32 v116, 0x3fb8aa3b, v11
	v_mul_u32_u24_e32 v113, 0x90, v10
	v_mul_u32_u24_e32 v114, 0x88, v10
	v_lshl_add_u64 v[106:107], s[2:3], 0, v[2:3]
	v_lshlrev_b32_e32 v118, 1, v13
	v_mov_b32_e32 v33, v32
	v_mov_b32_e32 v34, v32
	v_mov_b32_e32 v35, v32
	v_mov_b32_e32 v36, v32
	v_mov_b32_e32 v37, v32
	v_mov_b32_e32 v38, v32
	v_mov_b32_e32 v39, v32
	v_mov_b32_e32 v40, v32
	v_mov_b32_e32 v41, v32
	v_mov_b32_e32 v42, v32
	v_mov_b32_e32 v43, v32
	v_mov_b32_e32 v44, v32
	v_mov_b32_e32 v45, v32
	v_mov_b32_e32 v46, v32
	v_mov_b32_e32 v47, v32
	v_mov_b32_e32 v16, v32
	v_mov_b32_e32 v17, v32
	v_mov_b32_e32 v18, v32
	v_mov_b32_e32 v19, v32
	v_mov_b32_e32 v20, v32
	v_mov_b32_e32 v21, v32
	v_mov_b32_e32 v22, v32
	v_mov_b32_e32 v23, v32
	v_mov_b32_e32 v24, v32
	v_mov_b32_e32 v25, v32
	v_mov_b32_e32 v26, v32
	v_mov_b32_e32 v27, v32
	v_mov_b32_e32 v28, v32
	v_mov_b32_e32 v29, v32
	v_mov_b32_e32 v30, v32
	v_mov_b32_e32 v31, v32
	s_branch .LBB0_204
